# WKV scan: blocked decay - within 4-step blocks the per-column decay is folded into prep-scaled coefficient vectors (f32, algebraically identical), S*w multiply once per 4 steps, no per-step W read
# baseline (speedup 1.0000x reference)
.LBB0_540:
	s_lshl_b32 s51, s88, 7
	s_and_b32 s20, s51, 0xfffff000
	v_or_b32_e32 v2, s20, v59
	v_ashrrev_i32_e32 v3, 31, v2
	s_lshl_b32 s50, s4, 6
	v_lshlrev_b64 v[104:105], 10, v[2:3]
	v_or_b32_e32 v17, s50, v104
	s_andn2_b64 vcc, exec, s[2:3]
	v_or_b32_e32 v104, v17, v60
	s_cbranch_vccnz .LBB0_544
	v_lshlrev_b64 v[16:17], 1, v[104:105]
	v_lshl_add_u64 v[18:19], s[24:25], 0, v[16:17]
	v_lshl_add_u64 v[20:21], s[26:27], 0, v[16:17]
	global_load_dwordx2 v[18:19], v[18:19], off
	v_lshl_add_u64 v[22:23], s[28:29], 0, v[16:17]
	global_load_dwordx2 v[20:21], v[20:21], off
	v_lshl_add_u64 v[24:25], s[30:31], 0, v[16:17]
	v_lshl_add_u64 v[16:17], s[34:35], 0, v[16:17]
	global_load_dwordx2 v[22:23], v[22:23], off
	v_cmp_eq_u32_e32 vcc, 0, v0
	global_load_dwordx2 v[24:25], v[24:25], off
	s_waitcnt vmcnt(0)
	v_lshlrev_b32_e32 v28, 16, v20
	global_load_dwordx2 v[26:27], v[16:17], off
	v_and_b32_e32 v29, 0xffff0000, v20
	v_lshlrev_b32_e32 v30, 16, v21
	v_and_b32_e32 v31, 0xffff0000, v21
	v_lshlrev_b32_e32 v40, 16, v24
	v_and_b32_e32 v41, 0xffff0000, v24
	v_lshlrev_b32_e32 v42, 16, v25
	v_and_b32_e32 v43, 0xffff0000, v25
	v_pk_mul_f32 v[36:37], v[4:5], v[28:29]
	v_pk_mul_f32 v[38:39], v[6:7], v[30:31]
	v_lshlrev_b32_e32 v16, 16, v18
	v_and_b32_e32 v17, 0xffff0000, v18
	v_lshlrev_b32_e32 v18, 16, v19
	v_and_b32_e32 v19, 0xffff0000, v19
	v_lshlrev_b32_e32 v20, 16, v22
	v_and_b32_e32 v21, 0xffff0000, v22
	v_mul_f32_e32 v46, 0xbfb8aa3b, v40
	v_mul_f32_e32 v47, 0xbfb8aa3b, v41
	v_mul_f32_e32 v48, 0xbfb8aa3b, v42
	v_mul_f32_e32 v49, 0xbfb8aa3b, v43
	v_pk_mul_f32 v[40:41], v[38:39], v[38:39]
	v_pk_mul_f32 v[42:43], v[36:37], v[36:37]
	v_lshlrev_b32_e32 v22, 16, v23
	v_and_b32_e32 v23, 0xffff0000, v23
	ds_write_b128 v69, v[16:19]
	ds_write_b128 v69, v[20:23] offset:12288
	v_add_u32_e32 v197, 0x1d000, v69
	ds_write2_b32 v197, v21, v20 offset1:1
	ds_write2_b32 v197, v23, v22 offset0:2 offset1:3
	v_exp_f32_e32 v20, v46
	v_exp_f32_e32 v21, v47
	v_pk_mov_b32 v[46:47], v[42:43], v[40:41] op_sel:[1,0]
	v_mov_b32_e32 v43, v41
	v_exp_f32_e32 v22, v48
	v_exp_f32_e32 v23, v49
	ds_write_b128 v69, v[20:23] offset:4096
	s_waitcnt vmcnt(0)
	v_lshlrev_b32_e32 v32, 16, v26
	v_and_b32_e32 v33, 0xffff0000, v26
	v_lshlrev_b32_e32 v34, 16, v27
	v_and_b32_e32 v35, 0xffff0000, v27
	v_pk_add_f32 v[24:25], v[34:35], -1.0 op_sel_hi:[1,0]
	v_pk_add_f32 v[26:27], v[32:33], -1.0 op_sel_hi:[1,0]
	v_pk_fma_f32 v[24:25], v[10:11], v[24:25], 1.0 op_sel_hi:[1,1,0]
	v_pk_fma_f32 v[44:45], v[8:9], v[26:27], 1.0 op_sel_hi:[1,1,0]
	v_pk_mul_f32 v[26:27], v[24:25], v[30:31]
	v_pk_mul_f32 v[24:25], v[44:45], v[28:29]
	v_pk_add_f32 v[28:29], v[46:47], v[42:43]
	v_pk_mul_f32 v[16:17], v[24:25], v[16:17]
	v_pk_mul_f32 v[18:19], v[26:27], v[18:19]
	ds_write_b128 v69, v[24:27] offset:8192
	v_add_f32_e32 v24, v28, v29
	v_pk_mul_f32 v[18:19], v[14:15], v[18:19]
	v_pk_mul_f32 v[16:17], v[12:13], v[16:17]
	v_add_f32_dpp v24, v24, v24 quad_perm:[1,0,3,2] row_mask:0xf bank_mask:0xf bound_ctrl:1
	v_add_f32_e32 v16, v16, v17
	v_add_f32_e32 v17, v18, v19
	v_add_f32_dpp v18, v24, v24 quad_perm:[2,3,0,1] row_mask:0xf bank_mask:0xf bound_ctrl:1
	v_add_f32_e32 v16, v16, v17
	s_nop 0
	v_add_f32_dpp v17, v18, v18 row_half_mirror row_mask:0xf bank_mask:0xf bound_ctrl:1
	v_add_f32_dpp v16, v16, v16 quad_perm:[1,0,3,2] row_mask:0xf bank_mask:0xf bound_ctrl:1
	s_nop 0
	v_add_f32_dpp v17, v17, v17 row_mirror row_mask:0xf bank_mask:0xf bound_ctrl:1
	v_max_f32_e32 v17, 0x179abe15, v17
	v_rsq_f32_e32 v18, v17
	v_add_f32_dpp v16, v16, v16 quad_perm:[2,3,0,1] row_mask:0xf bank_mask:0xf bound_ctrl:1
	v_pk_mul_f32 v[20:21], v[38:39], v[18:19] op_sel_hi:[1,0]
	s_nop 0
	v_add_f32_dpp v16, v16, v16 row_half_mirror row_mask:0xf bank_mask:0xf bound_ctrl:1
	v_pk_mul_f32 v[18:19], v[36:37], v[18:19] op_sel_hi:[1,0]
	ds_write_b128 v69, v[18:21] offset:16384
	v_mov_b32_dpp v17, v16 row_mirror row_mask:0xf bank_mask:0xf bound_ctrl:1
	v_pk_mul_f32 v[20:21], v[20:21], v[34:35]
	v_pk_mul_f32 v[18:19], v[18:19], v[32:33]
	ds_write_b128 v69, v[18:21] offset:20480
	ds_read_b128 v[200:203], v69 offset:4096
	ds_read_b128 v[224:227], v69
	ds_read_b128 v[228:231], v69 offset:8192
	ds_read_b128 v[232:235], v69 offset:16384
	ds_read_b128 v[236:239], v69 offset:20480
	s_mov_b32 s98, 0xffff0000
	s_mov_b32 s99, 0xffff0000
	s_mov_b32 s100, 0
	s_mov_b32 s101, -1
	s_waitcnt lgkmcnt(4)
	v_mov_b32_e32 v204, v200
	v_mov_b32_e32 v205, v200
	s_nop 1
	v_permlane16_swap_b32_e32 v204, v205
	v_mul_f32_e32 v206, v204, v205
	v_bitop3_b32 v207, v204, v205, v200 bitop3:0x96
	v_cndmask_b32_e64 v207, 1.0, v207, s[98:99]
	v_mov_b32_e32 v208, v206
	v_mov_b32_e32 v209, v206
	s_nop 1
	v_permlane32_swap_b32_e32 v208, v209
	v_cndmask_b32_e64 v208, 1.0, v208, s[100:101]
	v_mul_f32_e32 v210, v207, v208
	v_mul_f32_e32 v214, v210, v200
	v_mov_b32_e32 v204, v201
	v_mov_b32_e32 v205, v201
	s_nop 1
	v_permlane16_swap_b32_e32 v204, v205
	v_mul_f32_e32 v206, v204, v205
	v_bitop3_b32 v207, v204, v205, v201 bitop3:0x96
	v_cndmask_b32_e64 v207, 1.0, v207, s[98:99]
	v_mov_b32_e32 v208, v206
	v_mov_b32_e32 v209, v206
	s_nop 1
	v_permlane32_swap_b32_e32 v208, v209
	v_cndmask_b32_e64 v208, 1.0, v208, s[100:101]
	v_mul_f32_e32 v211, v207, v208
	v_mul_f32_e32 v215, v211, v201
	v_mov_b32_e32 v204, v202
	v_mov_b32_e32 v205, v202
	s_nop 1
	v_permlane16_swap_b32_e32 v204, v205
	v_mul_f32_e32 v206, v204, v205
	v_bitop3_b32 v207, v204, v205, v202 bitop3:0x96
	v_cndmask_b32_e64 v207, 1.0, v207, s[98:99]
	v_mov_b32_e32 v208, v206
	v_mov_b32_e32 v209, v206
	s_nop 1
	v_permlane32_swap_b32_e32 v208, v209
	v_cndmask_b32_e64 v208, 1.0, v208, s[100:101]
	v_mul_f32_e32 v212, v207, v208
	v_mul_f32_e32 v216, v212, v202
	v_mov_b32_e32 v204, v203
	v_mov_b32_e32 v205, v203
	s_nop 1
	v_permlane16_swap_b32_e32 v204, v205
	v_mul_f32_e32 v206, v204, v205
	v_bitop3_b32 v207, v204, v205, v203 bitop3:0x96
	v_cndmask_b32_e64 v207, 1.0, v207, s[98:99]
	v_mov_b32_e32 v208, v206
	v_mov_b32_e32 v209, v206
	s_nop 1
	v_permlane32_swap_b32_e32 v208, v209
	v_cndmask_b32_e64 v208, 1.0, v208, s[100:101]
	v_mul_f32_e32 v213, v207, v208
	v_mul_f32_e32 v217, v213, v203
	v_rcp_f32_e32 v218, v214
	v_rcp_f32_e32 v219, v215
	v_rcp_f32_e32 v220, v216
	v_rcp_f32_e32 v221, v217
	v_cndmask_b32_e64 v204, v214, 1.0, s[98:99]
	v_cndmask_b32_e64 v240, v214, v204, s[100:101]
	v_cndmask_b32_e64 v204, v215, 1.0, s[98:99]
	v_cndmask_b32_e64 v241, v215, v204, s[100:101]
	v_cndmask_b32_e64 v204, v216, 1.0, s[98:99]
	v_cndmask_b32_e64 v242, v216, v204, s[100:101]
	v_cndmask_b32_e64 v204, v217, 1.0, s[98:99]
	v_cndmask_b32_e64 v243, v217, v204, s[100:101]
	s_waitcnt lgkmcnt(0)
	v_pk_mul_f32 v[224:225], v[224:225], v[240:241]
	v_pk_mul_f32 v[228:229], v[228:229], v[218:219]
	v_pk_mul_f32 v[232:233], v[232:233], v[210:211]
	v_pk_mul_f32 v[236:237], v[236:237], v[218:219]
	v_pk_mul_f32 v[226:227], v[226:227], v[242:243]
	v_pk_mul_f32 v[230:231], v[230:231], v[220:221]
	v_pk_mul_f32 v[234:235], v[234:235], v[212:213]
	v_pk_mul_f32 v[238:239], v[238:239], v[220:221]
	ds_write_b128 v69, v[224:227]
	ds_write_b128 v69, v[214:217] offset:4096
	ds_write_b128 v69, v[228:231] offset:8192
	ds_write_b128 v69, v[232:235] offset:16384
	ds_write_b128 v69, v[236:239] offset:20480
	s_and_saveexec_b64 s[2:3], vcc
	s_cbranch_execz .LBB0_543
	v_lshlrev_b64 v[2:3], 6, v[2:3]
	v_lshl_add_u64 v[2:3], s[38:39], 0, v[2:3]
	s_lshl_b32 s40, s4, 2
	v_lshl_add_u64 v[2:3], v[2:3], 0, s[40:41]
	v_add_f32_e32 v16, v16, v17
	global_store_dword v[2:3], v16, off

.LBB0_545:
	s_mul_i32 s4, s93, 0x6000
	s_lshl_b32 s5, s93, 14
	v_add_u32_e32 v2, s4, v194
	v_add_u32_e32 v3, s4, v195
	v_add_u32_e32 v0, s5, v196
	ds_read_b128 v[24:27], v2 offset:16384
	ds_read_b64 v[44:45], v3 offset:12288
	ds_read_b128 v[36:39], v2 offset:8192
	ds_read_b128 v[32:35], v2 offset:20480
	ds_read_b128 v[40:43], v2 offset:0
	ds_read_b128 v[144:147], v2 offset:16640
	ds_read_b64 v[164:165], v3 offset:12544
	ds_read_b128 v[156:159], v2 offset:8448
	ds_read_b128 v[152:155], v2 offset:20736
	s_waitcnt lgkmcnt(4)
	v_pk_mul_f32 v[46:47], v[16:17], v[24:25] op_sel_hi:[1,0]
	v_pk_fma_f32 v[46:47], v[18:19], v[24:25], v[46:47] op_sel:[0,1,0] op_sel_hi:[1,1,1]
	v_pk_fma_f32 v[46:47], v[20:21], v[26:27], v[46:47] op_sel_hi:[1,0,1]
	v_pk_fma_f32 v[46:47], v[22:23], v[26:27], v[46:47] op_sel:[0,1,0] op_sel_hi:[1,1,1]
	ds_read_b128 v[160:163], v2 offset:256
	v_pk_fma_f32 v[16:17], v[44:45], v[36:37], v[16:17] op_sel_hi:[1,0,1]
	v_add_f32_dpp v48, v47, v46 quad_perm:[1,0,3,2] row_mask:0xf bank_mask:0xf bound_ctrl:1
	v_pk_fma_f32 v[18:19], v[44:45], v[36:37], v[18:19] op_sel:[0,1,0] op_sel_hi:[1,1,1]
	s_nop 0
	v_add_f32_dpp v48, v48, v48 quad_perm:[2,3,0,1] row_mask:0xf bank_mask:0xf bound_ctrl:1
	v_pk_fma_f32 v[20:21], v[44:45], v[38:39], v[20:21] op_sel_hi:[1,0,1]
	s_nop 0
	v_add_f32_dpp v48, v48, v48 row_ror:4 row_mask:0xf bank_mask:0xf bound_ctrl:1
	v_pk_fma_f32 v[22:23], v[44:45], v[38:39], v[22:23] op_sel:[0,1,0] op_sel_hi:[1,1,1]
	s_nop 0
	v_add_f32_dpp v48, v48, v48 row_ror:8 row_mask:0xf bank_mask:0xf bound_ctrl:1
	s_nop 1
	v_mov_b32_dpp v49, v48 quad_perm:[1,0,3,2] row_mask:0xf bank_mask:0xf bound_ctrl:1
	v_pk_fma_f32 v[16:17], v[48:49], v[32:33], v[16:17] op_sel_hi:[1,0,1] neg_lo:[0,1,0] neg_hi:[0,1,0]
	v_pk_fma_f32 v[18:19], v[48:49], v[32:33], v[18:19] op_sel:[0,1,0] op_sel_hi:[1,1,1] neg_lo:[0,1,0] neg_hi:[0,1,0]
	v_pk_fma_f32 v[20:21], v[48:49], v[34:35], v[20:21] op_sel_hi:[1,0,1] neg_lo:[0,1,0] neg_hi:[0,1,0]
	v_pk_fma_f32 v[22:23], v[48:49], v[34:35], v[22:23] op_sel:[0,1,0] op_sel_hi:[1,1,1] neg_lo:[0,1,0] neg_hi:[0,1,0]
	ds_read_b128 v[24:27], v2 offset:16896
	ds_read_b64 v[44:45], v3 offset:12800
	ds_read_b128 v[36:39], v2 offset:8704
	ds_read_b128 v[32:35], v2 offset:20992
	s_waitcnt lgkmcnt(4)
	v_pk_mul_f32 v[46:47], v[16:17], v[144:145] op_sel_hi:[1,0]
	v_pk_mul_f32 v[50:51], v[16:17], v[40:41] op_sel_hi:[1,0]
	v_pk_fma_f32 v[46:47], v[18:19], v[144:145], v[46:47] op_sel:[0,1,0] op_sel_hi:[1,1,1]
	v_pk_fma_f32 v[50:51], v[18:19], v[40:41], v[50:51] op_sel:[0,1,0] op_sel_hi:[1,1,1]
	v_pk_fma_f32 v[46:47], v[20:21], v[146:147], v[46:47] op_sel_hi:[1,0,1]
	v_pk_fma_f32 v[50:51], v[20:21], v[42:43], v[50:51] op_sel_hi:[1,0,1]
	v_pk_fma_f32 v[46:47], v[22:23], v[146:147], v[46:47] op_sel:[0,1,0] op_sel_hi:[1,1,1]
	v_pk_fma_f32 v[50:51], v[22:23], v[42:43], v[50:51] op_sel:[0,1,0] op_sel_hi:[1,1,1]
	ds_read_b128 v[40:43], v2 offset:512
	v_pk_fma_f32 v[16:17], v[164:165], v[156:157], v[16:17] op_sel_hi:[1,0,1]
	v_add_f32_dpp v48, v47, v46 quad_perm:[1,0,3,2] row_mask:0xf bank_mask:0xf bound_ctrl:1
	v_add_f32_dpp v52, v51, v50 quad_perm:[1,0,3,2] row_mask:0xf bank_mask:0xf bound_ctrl:1
	v_pk_fma_f32 v[18:19], v[164:165], v[156:157], v[18:19] op_sel:[0,1,0] op_sel_hi:[1,1,1]
	v_add_f32_dpp v48, v48, v48 quad_perm:[2,3,0,1] row_mask:0xf bank_mask:0xf bound_ctrl:1
	v_pk_fma_f32 v[20:21], v[164:165], v[158:159], v[20:21] op_sel_hi:[1,0,1]
	s_nop 0
	v_add_f32_dpp v48, v48, v48 row_ror:4 row_mask:0xf bank_mask:0xf bound_ctrl:1
	v_pk_fma_f32 v[22:23], v[164:165], v[158:159], v[22:23] op_sel:[0,1,0] op_sel_hi:[1,1,1]
	s_nop 0
	v_add_f32_dpp v48, v48, v48 row_ror:8 row_mask:0xf bank_mask:0xf bound_ctrl:1
	s_nop 1
	v_mov_b32_dpp v49, v48 quad_perm:[1,0,3,2] row_mask:0xf bank_mask:0xf bound_ctrl:1
	v_pk_fma_f32 v[16:17], v[48:49], v[152:153], v[16:17] op_sel_hi:[1,0,1] neg_lo:[0,1,0] neg_hi:[0,1,0]
	v_pk_fma_f32 v[18:19], v[48:49], v[152:153], v[18:19] op_sel:[0,1,0] op_sel_hi:[1,1,1] neg_lo:[0,1,0] neg_hi:[0,1,0]
	v_pk_fma_f32 v[20:21], v[48:49], v[154:155], v[20:21] op_sel_hi:[1,0,1] neg_lo:[0,1,0] neg_hi:[0,1,0]
	v_pk_fma_f32 v[22:23], v[48:49], v[154:155], v[22:23] op_sel:[0,1,0] op_sel_hi:[1,1,1] neg_lo:[0,1,0] neg_hi:[0,1,0]
	ds_read_b128 v[144:147], v2 offset:17152
	ds_read_b64 v[164:165], v3 offset:13056
	ds_read_b128 v[156:159], v2 offset:8960
	ds_read_b128 v[148:151], v2 offset:4864
	ds_read_b128 v[152:155], v2 offset:21248
	s_waitcnt lgkmcnt(5)
	v_pk_mul_f32 v[46:47], v[16:17], v[24:25] op_sel_hi:[1,0]
	v_pk_mul_f32 v[50:51], v[16:17], v[160:161] op_sel_hi:[1,0]
	v_pk_fma_f32 v[46:47], v[18:19], v[24:25], v[46:47] op_sel:[0,1,0] op_sel_hi:[1,1,1]
	v_pk_fma_f32 v[50:51], v[18:19], v[160:161], v[50:51] op_sel:[0,1,0] op_sel_hi:[1,1,1]
	v_pk_fma_f32 v[46:47], v[20:21], v[26:27], v[46:47] op_sel_hi:[1,0,1]
	v_pk_fma_f32 v[50:51], v[20:21], v[162:163], v[50:51] op_sel_hi:[1,0,1]
	v_pk_fma_f32 v[46:47], v[22:23], v[26:27], v[46:47] op_sel:[0,1,0] op_sel_hi:[1,1,1]
	v_pk_fma_f32 v[50:51], v[22:23], v[162:163], v[50:51] op_sel:[0,1,0] op_sel_hi:[1,1,1]
	ds_read_b128 v[160:163], v2 offset:768
	v_pk_fma_f32 v[16:17], v[44:45], v[36:37], v[16:17] op_sel_hi:[1,0,1]
	v_add_f32_dpp v48, v47, v46 quad_perm:[1,0,3,2] row_mask:0xf bank_mask:0xf bound_ctrl:1
	v_add_f32_dpp v53, v51, v50 quad_perm:[1,0,3,2] row_mask:0xf bank_mask:0xf bound_ctrl:1
	v_pk_fma_f32 v[18:19], v[44:45], v[36:37], v[18:19] op_sel:[0,1,0] op_sel_hi:[1,1,1]
	v_add_f32_dpp v48, v48, v48 quad_perm:[2,3,0,1] row_mask:0xf bank_mask:0xf bound_ctrl:1
	ds_write2st64_b32 v0, v52, v53 offset0:192 offset1:196
	v_pk_fma_f32 v[20:21], v[44:45], v[38:39], v[20:21] op_sel_hi:[1,0,1]
	v_add_f32_dpp v48, v48, v48 row_ror:4 row_mask:0xf bank_mask:0xf bound_ctrl:1
	v_pk_fma_f32 v[22:23], v[44:45], v[38:39], v[22:23] op_sel:[0,1,0] op_sel_hi:[1,1,1]
	s_nop 0
	v_add_f32_dpp v48, v48, v48 row_ror:8 row_mask:0xf bank_mask:0xf bound_ctrl:1
	s_nop 1
	v_mov_b32_dpp v49, v48 quad_perm:[1,0,3,2] row_mask:0xf bank_mask:0xf bound_ctrl:1
	v_pk_fma_f32 v[16:17], v[48:49], v[32:33], v[16:17] op_sel_hi:[1,0,1] neg_lo:[0,1,0] neg_hi:[0,1,0]
	v_pk_fma_f32 v[18:19], v[48:49], v[32:33], v[18:19] op_sel:[0,1,0] op_sel_hi:[1,1,1] neg_lo:[0,1,0] neg_hi:[0,1,0]
	v_pk_fma_f32 v[20:21], v[48:49], v[34:35], v[20:21] op_sel_hi:[1,0,1] neg_lo:[0,1,0] neg_hi:[0,1,0]
	v_pk_fma_f32 v[22:23], v[48:49], v[34:35], v[22:23] op_sel:[0,1,0] op_sel_hi:[1,1,1] neg_lo:[0,1,0] neg_hi:[0,1,0]
	ds_read_b128 v[24:27], v2 offset:17408
	ds_read_b64 v[44:45], v3 offset:13312
	ds_read_b128 v[36:39], v2 offset:9216
	ds_read_b128 v[32:35], v2 offset:21504
	s_waitcnt lgkmcnt(5)
	v_pk_mul_f32 v[46:47], v[16:17], v[144:145] op_sel_hi:[1,0]
	v_pk_mul_f32 v[50:51], v[16:17], v[40:41] op_sel_hi:[1,0]
	v_pk_fma_f32 v[46:47], v[18:19], v[144:145], v[46:47] op_sel:[0,1,0] op_sel_hi:[1,1,1]
	v_pk_fma_f32 v[50:51], v[18:19], v[40:41], v[50:51] op_sel:[0,1,0] op_sel_hi:[1,1,1]
	v_pk_fma_f32 v[46:47], v[20:21], v[146:147], v[46:47] op_sel_hi:[1,0,1]
	v_pk_fma_f32 v[50:51], v[20:21], v[42:43], v[50:51] op_sel_hi:[1,0,1]
	v_pk_fma_f32 v[46:47], v[22:23], v[146:147], v[46:47] op_sel:[0,1,0] op_sel_hi:[1,1,1]
	v_pk_fma_f32 v[50:51], v[22:23], v[42:43], v[50:51] op_sel:[0,1,0] op_sel_hi:[1,1,1]
	ds_read_b128 v[40:43], v2 offset:1024
	v_pk_fma_f32 v[16:17], v[164:165], v[156:157], v[16:17] op_sel_hi:[1,0,1]
	v_add_f32_dpp v48, v47, v46 quad_perm:[1,0,3,2] row_mask:0xf bank_mask:0xf bound_ctrl:1
	v_add_f32_dpp v52, v51, v50 quad_perm:[1,0,3,2] row_mask:0xf bank_mask:0xf bound_ctrl:1
	v_pk_fma_f32 v[18:19], v[164:165], v[156:157], v[18:19] op_sel:[0,1,0] op_sel_hi:[1,1,1]
	v_add_f32_dpp v48, v48, v48 quad_perm:[2,3,0,1] row_mask:0xf bank_mask:0xf bound_ctrl:1
	v_pk_fma_f32 v[20:21], v[164:165], v[158:159], v[20:21] op_sel_hi:[1,0,1]
	s_nop 0
	v_add_f32_dpp v48, v48, v48 row_ror:4 row_mask:0xf bank_mask:0xf bound_ctrl:1
	v_pk_fma_f32 v[22:23], v[164:165], v[158:159], v[22:23] op_sel:[0,1,0] op_sel_hi:[1,1,1]
	s_nop 0
	v_add_f32_dpp v48, v48, v48 row_ror:8 row_mask:0xf bank_mask:0xf bound_ctrl:1
	s_nop 1
	v_mov_b32_dpp v49, v48 quad_perm:[1,0,3,2] row_mask:0xf bank_mask:0xf bound_ctrl:1
	v_pk_fma_f32 v[16:17], v[48:49], v[152:153], v[16:17] op_sel_hi:[1,0,1] neg_lo:[0,1,0] neg_hi:[0,1,0]
	v_pk_fma_f32 v[18:19], v[48:49], v[152:153], v[18:19] op_sel:[0,1,0] op_sel_hi:[1,1,1] neg_lo:[0,1,0] neg_hi:[0,1,0]
	v_pk_fma_f32 v[20:21], v[48:49], v[154:155], v[20:21] op_sel_hi:[1,0,1] neg_lo:[0,1,0] neg_hi:[0,1,0]
	v_pk_fma_f32 v[22:23], v[48:49], v[154:155], v[22:23] op_sel:[0,1,0] op_sel_hi:[1,1,1] neg_lo:[0,1,0] neg_hi:[0,1,0]
	v_pk_mul_f32 v[16:17], v[16:17], v[148:149] op_sel_hi:[1,0]
	v_pk_mul_f32 v[18:19], v[18:19], v[148:149] op_sel:[0,1] op_sel_hi:[1,1]
	v_pk_mul_f32 v[20:21], v[20:21], v[150:151] op_sel_hi:[1,0]
	v_pk_mul_f32 v[22:23], v[22:23], v[150:151] op_sel:[0,1] op_sel_hi:[1,1]
	ds_read_b128 v[144:147], v2 offset:17664
	ds_read_b64 v[164:165], v3 offset:13568
	ds_read_b128 v[156:159], v2 offset:9472
	ds_read_b128 v[152:155], v2 offset:21760
	s_waitcnt lgkmcnt(4)
	v_pk_mul_f32 v[46:47], v[16:17], v[24:25] op_sel_hi:[1,0]
	v_pk_mul_f32 v[50:51], v[16:17], v[160:161] op_sel_hi:[1,0]
	v_pk_fma_f32 v[46:47], v[18:19], v[24:25], v[46:47] op_sel:[0,1,0] op_sel_hi:[1,1,1]
	v_pk_fma_f32 v[50:51], v[18:19], v[160:161], v[50:51] op_sel:[0,1,0] op_sel_hi:[1,1,1]
	v_pk_fma_f32 v[46:47], v[20:21], v[26:27], v[46:47] op_sel_hi:[1,0,1]
	v_pk_fma_f32 v[50:51], v[20:21], v[162:163], v[50:51] op_sel_hi:[1,0,1]
	v_pk_fma_f32 v[46:47], v[22:23], v[26:27], v[46:47] op_sel:[0,1,0] op_sel_hi:[1,1,1]
	v_pk_fma_f32 v[50:51], v[22:23], v[162:163], v[50:51] op_sel:[0,1,0] op_sel_hi:[1,1,1]
	ds_read_b128 v[160:163], v2 offset:1280
	v_pk_fma_f32 v[16:17], v[44:45], v[36:37], v[16:17] op_sel_hi:[1,0,1]
	v_add_f32_dpp v48, v47, v46 quad_perm:[1,0,3,2] row_mask:0xf bank_mask:0xf bound_ctrl:1
	v_add_f32_dpp v53, v51, v50 quad_perm:[1,0,3,2] row_mask:0xf bank_mask:0xf bound_ctrl:1
	v_pk_fma_f32 v[18:19], v[44:45], v[36:37], v[18:19] op_sel:[0,1,0] op_sel_hi:[1,1,1]
	v_add_f32_dpp v48, v48, v48 quad_perm:[2,3,0,1] row_mask:0xf bank_mask:0xf bound_ctrl:1
	ds_write2st64_b32 v0, v52, v53 offset0:200 offset1:204
	v_pk_fma_f32 v[20:21], v[44:45], v[38:39], v[20:21] op_sel_hi:[1,0,1]
	v_add_f32_dpp v48, v48, v48 row_ror:4 row_mask:0xf bank_mask:0xf bound_ctrl:1
	v_pk_fma_f32 v[22:23], v[44:45], v[38:39], v[22:23] op_sel:[0,1,0] op_sel_hi:[1,1,1]
	s_nop 0
	v_add_f32_dpp v48, v48, v48 row_ror:8 row_mask:0xf bank_mask:0xf bound_ctrl:1
	s_nop 1
	v_mov_b32_dpp v49, v48 quad_perm:[1,0,3,2] row_mask:0xf bank_mask:0xf bound_ctrl:1
	v_pk_fma_f32 v[16:17], v[48:49], v[32:33], v[16:17] op_sel_hi:[1,0,1] neg_lo:[0,1,0] neg_hi:[0,1,0]
	v_pk_fma_f32 v[18:19], v[48:49], v[32:33], v[18:19] op_sel:[0,1,0] op_sel_hi:[1,1,1] neg_lo:[0,1,0] neg_hi:[0,1,0]
	v_pk_fma_f32 v[20:21], v[48:49], v[34:35], v[20:21] op_sel_hi:[1,0,1] neg_lo:[0,1,0] neg_hi:[0,1,0]
	v_pk_fma_f32 v[22:23], v[48:49], v[34:35], v[22:23] op_sel:[0,1,0] op_sel_hi:[1,1,1] neg_lo:[0,1,0] neg_hi:[0,1,0]
	ds_read_b128 v[24:27], v2 offset:17920
	ds_read_b64 v[44:45], v3 offset:13824
	ds_read_b128 v[36:39], v2 offset:9728
	ds_read_b128 v[32:35], v2 offset:22016
	s_waitcnt lgkmcnt(5)
	v_pk_mul_f32 v[46:47], v[16:17], v[144:145] op_sel_hi:[1,0]
	v_pk_mul_f32 v[50:51], v[16:17], v[40:41] op_sel_hi:[1,0]
	v_pk_fma_f32 v[46:47], v[18:19], v[144:145], v[46:47] op_sel:[0,1,0] op_sel_hi:[1,1,1]
	v_pk_fma_f32 v[50:51], v[18:19], v[40:41], v[50:51] op_sel:[0,1,0] op_sel_hi:[1,1,1]
	v_pk_fma_f32 v[46:47], v[20:21], v[146:147], v[46:47] op_sel_hi:[1,0,1]
	v_pk_fma_f32 v[50:51], v[20:21], v[42:43], v[50:51] op_sel_hi:[1,0,1]
	v_pk_fma_f32 v[46:47], v[22:23], v[146:147], v[46:47] op_sel:[0,1,0] op_sel_hi:[1,1,1]
	v_pk_fma_f32 v[50:51], v[22:23], v[42:43], v[50:51] op_sel:[0,1,0] op_sel_hi:[1,1,1]
	ds_read_b128 v[40:43], v2 offset:1536
	v_pk_fma_f32 v[16:17], v[164:165], v[156:157], v[16:17] op_sel_hi:[1,0,1]
	v_add_f32_dpp v48, v47, v46 quad_perm:[1,0,3,2] row_mask:0xf bank_mask:0xf bound_ctrl:1
	v_add_f32_dpp v52, v51, v50 quad_perm:[1,0,3,2] row_mask:0xf bank_mask:0xf bound_ctrl:1
	v_pk_fma_f32 v[18:19], v[164:165], v[156:157], v[18:19] op_sel:[0,1,0] op_sel_hi:[1,1,1]
	v_add_f32_dpp v48, v48, v48 quad_perm:[2,3,0,1] row_mask:0xf bank_mask:0xf bound_ctrl:1
	v_pk_fma_f32 v[20:21], v[164:165], v[158:159], v[20:21] op_sel_hi:[1,0,1]
	s_nop 0
	v_add_f32_dpp v48, v48, v48 row_ror:4 row_mask:0xf bank_mask:0xf bound_ctrl:1
	v_pk_fma_f32 v[22:23], v[164:165], v[158:159], v[22:23] op_sel:[0,1,0] op_sel_hi:[1,1,1]
	s_nop 0
	v_add_f32_dpp v48, v48, v48 row_ror:8 row_mask:0xf bank_mask:0xf bound_ctrl:1
	s_nop 1
	v_mov_b32_dpp v49, v48 quad_perm:[1,0,3,2] row_mask:0xf bank_mask:0xf bound_ctrl:1
	v_pk_fma_f32 v[16:17], v[48:49], v[152:153], v[16:17] op_sel_hi:[1,0,1] neg_lo:[0,1,0] neg_hi:[0,1,0]
	v_pk_fma_f32 v[18:19], v[48:49], v[152:153], v[18:19] op_sel:[0,1,0] op_sel_hi:[1,1,1] neg_lo:[0,1,0] neg_hi:[0,1,0]
	v_pk_fma_f32 v[20:21], v[48:49], v[154:155], v[20:21] op_sel_hi:[1,0,1] neg_lo:[0,1,0] neg_hi:[0,1,0]
	v_pk_fma_f32 v[22:23], v[48:49], v[154:155], v[22:23] op_sel:[0,1,0] op_sel_hi:[1,1,1] neg_lo:[0,1,0] neg_hi:[0,1,0]
	ds_read_b128 v[144:147], v2 offset:18176
	ds_read_b64 v[164:165], v3 offset:14080
	ds_read_b128 v[156:159], v2 offset:9984
	ds_read_b128 v[148:151], v2 offset:5888
	ds_read_b128 v[152:155], v2 offset:22272
	s_waitcnt lgkmcnt(5)
	v_pk_mul_f32 v[46:47], v[16:17], v[24:25] op_sel_hi:[1,0]
	v_pk_mul_f32 v[50:51], v[16:17], v[160:161] op_sel_hi:[1,0]
	v_pk_fma_f32 v[46:47], v[18:19], v[24:25], v[46:47] op_sel:[0,1,0] op_sel_hi:[1,1,1]
	v_pk_fma_f32 v[50:51], v[18:19], v[160:161], v[50:51] op_sel:[0,1,0] op_sel_hi:[1,1,1]
	v_pk_fma_f32 v[46:47], v[20:21], v[26:27], v[46:47] op_sel_hi:[1,0,1]
	v_pk_fma_f32 v[50:51], v[20:21], v[162:163], v[50:51] op_sel_hi:[1,0,1]
	v_pk_fma_f32 v[46:47], v[22:23], v[26:27], v[46:47] op_sel:[0,1,0] op_sel_hi:[1,1,1]
	v_pk_fma_f32 v[50:51], v[22:23], v[162:163], v[50:51] op_sel:[0,1,0] op_sel_hi:[1,1,1]
	ds_read_b128 v[160:163], v2 offset:1792
	v_pk_fma_f32 v[16:17], v[44:45], v[36:37], v[16:17] op_sel_hi:[1,0,1]
	v_add_f32_dpp v48, v47, v46 quad_perm:[1,0,3,2] row_mask:0xf bank_mask:0xf bound_ctrl:1
	v_add_f32_dpp v53, v51, v50 quad_perm:[1,0,3,2] row_mask:0xf bank_mask:0xf bound_ctrl:1
	v_pk_fma_f32 v[18:19], v[44:45], v[36:37], v[18:19] op_sel:[0,1,0] op_sel_hi:[1,1,1]
	v_add_f32_dpp v48, v48, v48 quad_perm:[2,3,0,1] row_mask:0xf bank_mask:0xf bound_ctrl:1
	ds_write2st64_b32 v0, v52, v53 offset0:208 offset1:212
	v_pk_fma_f32 v[20:21], v[44:45], v[38:39], v[20:21] op_sel_hi:[1,0,1]
	v_add_f32_dpp v48, v48, v48 row_ror:4 row_mask:0xf bank_mask:0xf bound_ctrl:1
	v_pk_fma_f32 v[22:23], v[44:45], v[38:39], v[22:23] op_sel:[0,1,0] op_sel_hi:[1,1,1]
	s_nop 0
	v_add_f32_dpp v48, v48, v48 row_ror:8 row_mask:0xf bank_mask:0xf bound_ctrl:1
	s_nop 1
	v_mov_b32_dpp v49, v48 quad_perm:[1,0,3,2] row_mask:0xf bank_mask:0xf bound_ctrl:1
	v_pk_fma_f32 v[16:17], v[48:49], v[32:33], v[16:17] op_sel_hi:[1,0,1] neg_lo:[0,1,0] neg_hi:[0,1,0]
	v_pk_fma_f32 v[18:19], v[48:49], v[32:33], v[18:19] op_sel:[0,1,0] op_sel_hi:[1,1,1] neg_lo:[0,1,0] neg_hi:[0,1,0]
	v_pk_fma_f32 v[20:21], v[48:49], v[34:35], v[20:21] op_sel_hi:[1,0,1] neg_lo:[0,1,0] neg_hi:[0,1,0]
	v_pk_fma_f32 v[22:23], v[48:49], v[34:35], v[22:23] op_sel:[0,1,0] op_sel_hi:[1,1,1] neg_lo:[0,1,0] neg_hi:[0,1,0]
	ds_read_b128 v[24:27], v2 offset:18432
	ds_read_b64 v[44:45], v3 offset:14336
	ds_read_b128 v[36:39], v2 offset:10240
	ds_read_b128 v[32:35], v2 offset:22528
	s_waitcnt lgkmcnt(5)
	v_pk_mul_f32 v[46:47], v[16:17], v[144:145] op_sel_hi:[1,0]
	v_pk_mul_f32 v[50:51], v[16:17], v[40:41] op_sel_hi:[1,0]
	v_pk_fma_f32 v[46:47], v[18:19], v[144:145], v[46:47] op_sel:[0,1,0] op_sel_hi:[1,1,1]
	v_pk_fma_f32 v[50:51], v[18:19], v[40:41], v[50:51] op_sel:[0,1,0] op_sel_hi:[1,1,1]
	v_pk_fma_f32 v[46:47], v[20:21], v[146:147], v[46:47] op_sel_hi:[1,0,1]
	v_pk_fma_f32 v[50:51], v[20:21], v[42:43], v[50:51] op_sel_hi:[1,0,1]
	v_pk_fma_f32 v[46:47], v[22:23], v[146:147], v[46:47] op_sel:[0,1,0] op_sel_hi:[1,1,1]
	v_pk_fma_f32 v[50:51], v[22:23], v[42:43], v[50:51] op_sel:[0,1,0] op_sel_hi:[1,1,1]
	ds_read_b128 v[40:43], v2 offset:2048
	v_pk_fma_f32 v[16:17], v[164:165], v[156:157], v[16:17] op_sel_hi:[1,0,1]
	v_add_f32_dpp v48, v47, v46 quad_perm:[1,0,3,2] row_mask:0xf bank_mask:0xf bound_ctrl:1
	v_add_f32_dpp v52, v51, v50 quad_perm:[1,0,3,2] row_mask:0xf bank_mask:0xf bound_ctrl:1
	v_pk_fma_f32 v[18:19], v[164:165], v[156:157], v[18:19] op_sel:[0,1,0] op_sel_hi:[1,1,1]
	v_add_f32_dpp v48, v48, v48 quad_perm:[2,3,0,1] row_mask:0xf bank_mask:0xf bound_ctrl:1
	v_pk_fma_f32 v[20:21], v[164:165], v[158:159], v[20:21] op_sel_hi:[1,0,1]
	s_nop 0
	v_add_f32_dpp v48, v48, v48 row_ror:4 row_mask:0xf bank_mask:0xf bound_ctrl:1
	v_pk_fma_f32 v[22:23], v[164:165], v[158:159], v[22:23] op_sel:[0,1,0] op_sel_hi:[1,1,1]
	s_nop 0
	v_add_f32_dpp v48, v48, v48 row_ror:8 row_mask:0xf bank_mask:0xf bound_ctrl:1
	s_nop 1
	v_mov_b32_dpp v49, v48 quad_perm:[1,0,3,2] row_mask:0xf bank_mask:0xf bound_ctrl:1
	v_pk_fma_f32 v[16:17], v[48:49], v[152:153], v[16:17] op_sel_hi:[1,0,1] neg_lo:[0,1,0] neg_hi:[0,1,0]
	v_pk_fma_f32 v[18:19], v[48:49], v[152:153], v[18:19] op_sel:[0,1,0] op_sel_hi:[1,1,1] neg_lo:[0,1,0] neg_hi:[0,1,0]
	v_pk_fma_f32 v[20:21], v[48:49], v[154:155], v[20:21] op_sel_hi:[1,0,1] neg_lo:[0,1,0] neg_hi:[0,1,0]
	v_pk_fma_f32 v[22:23], v[48:49], v[154:155], v[22:23] op_sel:[0,1,0] op_sel_hi:[1,1,1] neg_lo:[0,1,0] neg_hi:[0,1,0]
	v_pk_mul_f32 v[16:17], v[16:17], v[148:149] op_sel_hi:[1,0]
	v_pk_mul_f32 v[18:19], v[18:19], v[148:149] op_sel:[0,1] op_sel_hi:[1,1]
	v_pk_mul_f32 v[20:21], v[20:21], v[150:151] op_sel_hi:[1,0]
	v_pk_mul_f32 v[22:23], v[22:23], v[150:151] op_sel:[0,1] op_sel_hi:[1,1]
	ds_read_b128 v[144:147], v2 offset:18688
	ds_read_b64 v[164:165], v3 offset:14592
	ds_read_b128 v[156:159], v2 offset:10496
	ds_read_b128 v[152:155], v2 offset:22784
	s_waitcnt lgkmcnt(4)
	v_pk_mul_f32 v[46:47], v[16:17], v[24:25] op_sel_hi:[1,0]
	v_pk_mul_f32 v[50:51], v[16:17], v[160:161] op_sel_hi:[1,0]
	v_pk_fma_f32 v[46:47], v[18:19], v[24:25], v[46:47] op_sel:[0,1,0] op_sel_hi:[1,1,1]
	v_pk_fma_f32 v[50:51], v[18:19], v[160:161], v[50:51] op_sel:[0,1,0] op_sel_hi:[1,1,1]
	v_pk_fma_f32 v[46:47], v[20:21], v[26:27], v[46:47] op_sel_hi:[1,0,1]
	v_pk_fma_f32 v[50:51], v[20:21], v[162:163], v[50:51] op_sel_hi:[1,0,1]
	v_pk_fma_f32 v[46:47], v[22:23], v[26:27], v[46:47] op_sel:[0,1,0] op_sel_hi:[1,1,1]
	v_pk_fma_f32 v[50:51], v[22:23], v[162:163], v[50:51] op_sel:[0,1,0] op_sel_hi:[1,1,1]
	ds_read_b128 v[160:163], v2 offset:2304
	v_pk_fma_f32 v[16:17], v[44:45], v[36:37], v[16:17] op_sel_hi:[1,0,1]
	v_add_f32_dpp v48, v47, v46 quad_perm:[1,0,3,2] row_mask:0xf bank_mask:0xf bound_ctrl:1
	v_add_f32_dpp v53, v51, v50 quad_perm:[1,0,3,2] row_mask:0xf bank_mask:0xf bound_ctrl:1
	v_pk_fma_f32 v[18:19], v[44:45], v[36:37], v[18:19] op_sel:[0,1,0] op_sel_hi:[1,1,1]
	v_add_f32_dpp v48, v48, v48 quad_perm:[2,3,0,1] row_mask:0xf bank_mask:0xf bound_ctrl:1
	ds_write2st64_b32 v0, v52, v53 offset0:216 offset1:220
	v_pk_fma_f32 v[20:21], v[44:45], v[38:39], v[20:21] op_sel_hi:[1,0,1]
	v_add_f32_dpp v48, v48, v48 row_ror:4 row_mask:0xf bank_mask:0xf bound_ctrl:1
	v_pk_fma_f32 v[22:23], v[44:45], v[38:39], v[22:23] op_sel:[0,1,0] op_sel_hi:[1,1,1]
	s_nop 0
	v_add_f32_dpp v48, v48, v48 row_ror:8 row_mask:0xf bank_mask:0xf bound_ctrl:1
	s_nop 1
	v_mov_b32_dpp v49, v48 quad_perm:[1,0,3,2] row_mask:0xf bank_mask:0xf bound_ctrl:1
	v_pk_fma_f32 v[16:17], v[48:49], v[32:33], v[16:17] op_sel_hi:[1,0,1] neg_lo:[0,1,0] neg_hi:[0,1,0]
	v_pk_fma_f32 v[18:19], v[48:49], v[32:33], v[18:19] op_sel:[0,1,0] op_sel_hi:[1,1,1] neg_lo:[0,1,0] neg_hi:[0,1,0]
	v_pk_fma_f32 v[20:21], v[48:49], v[34:35], v[20:21] op_sel_hi:[1,0,1] neg_lo:[0,1,0] neg_hi:[0,1,0]
	v_pk_fma_f32 v[22:23], v[48:49], v[34:35], v[22:23] op_sel:[0,1,0] op_sel_hi:[1,1,1] neg_lo:[0,1,0] neg_hi:[0,1,0]
	ds_read_b128 v[24:27], v2 offset:18944
	ds_read_b64 v[44:45], v3 offset:14848
	ds_read_b128 v[36:39], v2 offset:10752
	ds_read_b128 v[32:35], v2 offset:23040
	s_waitcnt lgkmcnt(5)
	v_pk_mul_f32 v[46:47], v[16:17], v[144:145] op_sel_hi:[1,0]
	v_pk_mul_f32 v[50:51], v[16:17], v[40:41] op_sel_hi:[1,0]
	v_pk_fma_f32 v[46:47], v[18:19], v[144:145], v[46:47] op_sel:[0,1,0] op_sel_hi:[1,1,1]
	v_pk_fma_f32 v[50:51], v[18:19], v[40:41], v[50:51] op_sel:[0,1,0] op_sel_hi:[1,1,1]
	v_pk_fma_f32 v[46:47], v[20:21], v[146:147], v[46:47] op_sel_hi:[1,0,1]
	v_pk_fma_f32 v[50:51], v[20:21], v[42:43], v[50:51] op_sel_hi:[1,0,1]
	v_pk_fma_f32 v[46:47], v[22:23], v[146:147], v[46:47] op_sel:[0,1,0] op_sel_hi:[1,1,1]
	v_pk_fma_f32 v[50:51], v[22:23], v[42:43], v[50:51] op_sel:[0,1,0] op_sel_hi:[1,1,1]
	ds_read_b128 v[40:43], v2 offset:2560
	v_pk_fma_f32 v[16:17], v[164:165], v[156:157], v[16:17] op_sel_hi:[1,0,1]
	v_add_f32_dpp v48, v47, v46 quad_perm:[1,0,3,2] row_mask:0xf bank_mask:0xf bound_ctrl:1
	v_add_f32_dpp v52, v51, v50 quad_perm:[1,0,3,2] row_mask:0xf bank_mask:0xf bound_ctrl:1
	v_pk_fma_f32 v[18:19], v[164:165], v[156:157], v[18:19] op_sel:[0,1,0] op_sel_hi:[1,1,1]
	v_add_f32_dpp v48, v48, v48 quad_perm:[2,3,0,1] row_mask:0xf bank_mask:0xf bound_ctrl:1
	v_pk_fma_f32 v[20:21], v[164:165], v[158:159], v[20:21] op_sel_hi:[1,0,1]
	s_nop 0
	v_add_f32_dpp v48, v48, v48 row_ror:4 row_mask:0xf bank_mask:0xf bound_ctrl:1
	v_pk_fma_f32 v[22:23], v[164:165], v[158:159], v[22:23] op_sel:[0,1,0] op_sel_hi:[1,1,1]
	s_nop 0
	v_add_f32_dpp v48, v48, v48 row_ror:8 row_mask:0xf bank_mask:0xf bound_ctrl:1
	s_nop 1
	v_mov_b32_dpp v49, v48 quad_perm:[1,0,3,2] row_mask:0xf bank_mask:0xf bound_ctrl:1
	v_pk_fma_f32 v[16:17], v[48:49], v[152:153], v[16:17] op_sel_hi:[1,0,1] neg_lo:[0,1,0] neg_hi:[0,1,0]
	v_pk_fma_f32 v[18:19], v[48:49], v[152:153], v[18:19] op_sel:[0,1,0] op_sel_hi:[1,1,1] neg_lo:[0,1,0] neg_hi:[0,1,0]
	v_pk_fma_f32 v[20:21], v[48:49], v[154:155], v[20:21] op_sel_hi:[1,0,1] neg_lo:[0,1,0] neg_hi:[0,1,0]
	v_pk_fma_f32 v[22:23], v[48:49], v[154:155], v[22:23] op_sel:[0,1,0] op_sel_hi:[1,1,1] neg_lo:[0,1,0] neg_hi:[0,1,0]
	ds_read_b128 v[144:147], v2 offset:19200
	ds_read_b64 v[164:165], v3 offset:15104
	ds_read_b128 v[156:159], v2 offset:11008
	ds_read_b128 v[148:151], v2 offset:6912
	ds_read_b128 v[152:155], v2 offset:23296
	s_waitcnt lgkmcnt(5)
	v_pk_mul_f32 v[46:47], v[16:17], v[24:25] op_sel_hi:[1,0]
	v_pk_mul_f32 v[50:51], v[16:17], v[160:161] op_sel_hi:[1,0]
	v_pk_fma_f32 v[46:47], v[18:19], v[24:25], v[46:47] op_sel:[0,1,0] op_sel_hi:[1,1,1]
	v_pk_fma_f32 v[50:51], v[18:19], v[160:161], v[50:51] op_sel:[0,1,0] op_sel_hi:[1,1,1]
	v_pk_fma_f32 v[46:47], v[20:21], v[26:27], v[46:47] op_sel_hi:[1,0,1]
	v_pk_fma_f32 v[50:51], v[20:21], v[162:163], v[50:51] op_sel_hi:[1,0,1]
	v_pk_fma_f32 v[46:47], v[22:23], v[26:27], v[46:47] op_sel:[0,1,0] op_sel_hi:[1,1,1]
	v_pk_fma_f32 v[50:51], v[22:23], v[162:163], v[50:51] op_sel:[0,1,0] op_sel_hi:[1,1,1]
	ds_read_b128 v[160:163], v2 offset:2816
	v_pk_fma_f32 v[16:17], v[44:45], v[36:37], v[16:17] op_sel_hi:[1,0,1]
	v_add_f32_dpp v48, v47, v46 quad_perm:[1,0,3,2] row_mask:0xf bank_mask:0xf bound_ctrl:1
	v_add_f32_dpp v53, v51, v50 quad_perm:[1,0,3,2] row_mask:0xf bank_mask:0xf bound_ctrl:1
	v_pk_fma_f32 v[18:19], v[44:45], v[36:37], v[18:19] op_sel:[0,1,0] op_sel_hi:[1,1,1]
	v_add_f32_dpp v48, v48, v48 quad_perm:[2,3,0,1] row_mask:0xf bank_mask:0xf bound_ctrl:1
	ds_write2st64_b32 v0, v52, v53 offset0:224 offset1:228
	v_pk_fma_f32 v[20:21], v[44:45], v[38:39], v[20:21] op_sel_hi:[1,0,1]
	v_add_f32_dpp v48, v48, v48 row_ror:4 row_mask:0xf bank_mask:0xf bound_ctrl:1
	v_pk_fma_f32 v[22:23], v[44:45], v[38:39], v[22:23] op_sel:[0,1,0] op_sel_hi:[1,1,1]
	s_nop 0
	v_add_f32_dpp v48, v48, v48 row_ror:8 row_mask:0xf bank_mask:0xf bound_ctrl:1
	s_nop 1
	v_mov_b32_dpp v49, v48 quad_perm:[1,0,3,2] row_mask:0xf bank_mask:0xf bound_ctrl:1
	v_pk_fma_f32 v[16:17], v[48:49], v[32:33], v[16:17] op_sel_hi:[1,0,1] neg_lo:[0,1,0] neg_hi:[0,1,0]
	v_pk_fma_f32 v[18:19], v[48:49], v[32:33], v[18:19] op_sel:[0,1,0] op_sel_hi:[1,1,1] neg_lo:[0,1,0] neg_hi:[0,1,0]
	v_pk_fma_f32 v[20:21], v[48:49], v[34:35], v[20:21] op_sel_hi:[1,0,1] neg_lo:[0,1,0] neg_hi:[0,1,0]
	v_pk_fma_f32 v[22:23], v[48:49], v[34:35], v[22:23] op_sel:[0,1,0] op_sel_hi:[1,1,1] neg_lo:[0,1,0] neg_hi:[0,1,0]
	ds_read_b128 v[24:27], v2 offset:19456
	ds_read_b64 v[44:45], v3 offset:15360
	ds_read_b128 v[36:39], v2 offset:11264
	ds_read_b128 v[32:35], v2 offset:23552
	s_waitcnt lgkmcnt(5)
	v_pk_mul_f32 v[46:47], v[16:17], v[144:145] op_sel_hi:[1,0]
	v_pk_mul_f32 v[50:51], v[16:17], v[40:41] op_sel_hi:[1,0]
	v_pk_fma_f32 v[46:47], v[18:19], v[144:145], v[46:47] op_sel:[0,1,0] op_sel_hi:[1,1,1]
	v_pk_fma_f32 v[50:51], v[18:19], v[40:41], v[50:51] op_sel:[0,1,0] op_sel_hi:[1,1,1]
	v_pk_fma_f32 v[46:47], v[20:21], v[146:147], v[46:47] op_sel_hi:[1,0,1]
	v_pk_fma_f32 v[50:51], v[20:21], v[42:43], v[50:51] op_sel_hi:[1,0,1]
	v_pk_fma_f32 v[46:47], v[22:23], v[146:147], v[46:47] op_sel:[0,1,0] op_sel_hi:[1,1,1]
	v_pk_fma_f32 v[50:51], v[22:23], v[42:43], v[50:51] op_sel:[0,1,0] op_sel_hi:[1,1,1]
	ds_read_b128 v[40:43], v2 offset:3072
	v_pk_fma_f32 v[16:17], v[164:165], v[156:157], v[16:17] op_sel_hi:[1,0,1]
	v_add_f32_dpp v48, v47, v46 quad_perm:[1,0,3,2] row_mask:0xf bank_mask:0xf bound_ctrl:1
	v_add_f32_dpp v52, v51, v50 quad_perm:[1,0,3,2] row_mask:0xf bank_mask:0xf bound_ctrl:1
	v_pk_fma_f32 v[18:19], v[164:165], v[156:157], v[18:19] op_sel:[0,1,0] op_sel_hi:[1,1,1]
	v_add_f32_dpp v48, v48, v48 quad_perm:[2,3,0,1] row_mask:0xf bank_mask:0xf bound_ctrl:1
	v_pk_fma_f32 v[20:21], v[164:165], v[158:159], v[20:21] op_sel_hi:[1,0,1]
	s_nop 0
	v_add_f32_dpp v48, v48, v48 row_ror:4 row_mask:0xf bank_mask:0xf bound_ctrl:1
	v_pk_fma_f32 v[22:23], v[164:165], v[158:159], v[22:23] op_sel:[0,1,0] op_sel_hi:[1,1,1]
	s_nop 0
	v_add_f32_dpp v48, v48, v48 row_ror:8 row_mask:0xf bank_mask:0xf bound_ctrl:1
	s_nop 1
	v_mov_b32_dpp v49, v48 quad_perm:[1,0,3,2] row_mask:0xf bank_mask:0xf bound_ctrl:1
	v_pk_fma_f32 v[16:17], v[48:49], v[152:153], v[16:17] op_sel_hi:[1,0,1] neg_lo:[0,1,0] neg_hi:[0,1,0]
	v_pk_fma_f32 v[18:19], v[48:49], v[152:153], v[18:19] op_sel:[0,1,0] op_sel_hi:[1,1,1] neg_lo:[0,1,0] neg_hi:[0,1,0]
	v_pk_fma_f32 v[20:21], v[48:49], v[154:155], v[20:21] op_sel_hi:[1,0,1] neg_lo:[0,1,0] neg_hi:[0,1,0]
	v_pk_fma_f32 v[22:23], v[48:49], v[154:155], v[22:23] op_sel:[0,1,0] op_sel_hi:[1,1,1] neg_lo:[0,1,0] neg_hi:[0,1,0]
	v_pk_mul_f32 v[16:17], v[16:17], v[148:149] op_sel_hi:[1,0]
	v_pk_mul_f32 v[18:19], v[18:19], v[148:149] op_sel:[0,1] op_sel_hi:[1,1]
	v_pk_mul_f32 v[20:21], v[20:21], v[150:151] op_sel_hi:[1,0]
	v_pk_mul_f32 v[22:23], v[22:23], v[150:151] op_sel:[0,1] op_sel_hi:[1,1]
	ds_read_b128 v[144:147], v2 offset:19712
	ds_read_b64 v[164:165], v3 offset:15616
	ds_read_b128 v[156:159], v2 offset:11520
	ds_read_b128 v[152:155], v2 offset:23808
	s_waitcnt lgkmcnt(4)
	v_pk_mul_f32 v[46:47], v[16:17], v[24:25] op_sel_hi:[1,0]
	v_pk_mul_f32 v[50:51], v[16:17], v[160:161] op_sel_hi:[1,0]
	v_pk_fma_f32 v[46:47], v[18:19], v[24:25], v[46:47] op_sel:[0,1,0] op_sel_hi:[1,1,1]
	v_pk_fma_f32 v[50:51], v[18:19], v[160:161], v[50:51] op_sel:[0,1,0] op_sel_hi:[1,1,1]
	v_pk_fma_f32 v[46:47], v[20:21], v[26:27], v[46:47] op_sel_hi:[1,0,1]
	v_pk_fma_f32 v[50:51], v[20:21], v[162:163], v[50:51] op_sel_hi:[1,0,1]
	v_pk_fma_f32 v[46:47], v[22:23], v[26:27], v[46:47] op_sel:[0,1,0] op_sel_hi:[1,1,1]
	v_pk_fma_f32 v[50:51], v[22:23], v[162:163], v[50:51] op_sel:[0,1,0] op_sel_hi:[1,1,1]
	ds_read_b128 v[160:163], v2 offset:3328
	v_pk_fma_f32 v[16:17], v[44:45], v[36:37], v[16:17] op_sel_hi:[1,0,1]
	v_add_f32_dpp v48, v47, v46 quad_perm:[1,0,3,2] row_mask:0xf bank_mask:0xf bound_ctrl:1
	v_add_f32_dpp v53, v51, v50 quad_perm:[1,0,3,2] row_mask:0xf bank_mask:0xf bound_ctrl:1
	v_pk_fma_f32 v[18:19], v[44:45], v[36:37], v[18:19] op_sel:[0,1,0] op_sel_hi:[1,1,1]
	v_add_f32_dpp v48, v48, v48 quad_perm:[2,3,0,1] row_mask:0xf bank_mask:0xf bound_ctrl:1
	ds_write2st64_b32 v0, v52, v53 offset0:232 offset1:236
	v_pk_fma_f32 v[20:21], v[44:45], v[38:39], v[20:21] op_sel_hi:[1,0,1]
	v_add_f32_dpp v48, v48, v48 row_ror:4 row_mask:0xf bank_mask:0xf bound_ctrl:1
	v_pk_fma_f32 v[22:23], v[44:45], v[38:39], v[22:23] op_sel:[0,1,0] op_sel_hi:[1,1,1]
	s_nop 0
	v_add_f32_dpp v48, v48, v48 row_ror:8 row_mask:0xf bank_mask:0xf bound_ctrl:1
	s_nop 1
	v_mov_b32_dpp v49, v48 quad_perm:[1,0,3,2] row_mask:0xf bank_mask:0xf bound_ctrl:1
	v_pk_fma_f32 v[16:17], v[48:49], v[32:33], v[16:17] op_sel_hi:[1,0,1] neg_lo:[0,1,0] neg_hi:[0,1,0]
	v_pk_fma_f32 v[18:19], v[48:49], v[32:33], v[18:19] op_sel:[0,1,0] op_sel_hi:[1,1,1] neg_lo:[0,1,0] neg_hi:[0,1,0]
	v_pk_fma_f32 v[20:21], v[48:49], v[34:35], v[20:21] op_sel_hi:[1,0,1] neg_lo:[0,1,0] neg_hi:[0,1,0]
	v_pk_fma_f32 v[22:23], v[48:49], v[34:35], v[22:23] op_sel:[0,1,0] op_sel_hi:[1,1,1] neg_lo:[0,1,0] neg_hi:[0,1,0]
	ds_read_b128 v[24:27], v2 offset:19968
	ds_read_b64 v[44:45], v3 offset:15872
	ds_read_b128 v[36:39], v2 offset:11776
	ds_read_b128 v[32:35], v2 offset:24064
	s_waitcnt lgkmcnt(5)
	v_pk_mul_f32 v[46:47], v[16:17], v[144:145] op_sel_hi:[1,0]
	v_pk_mul_f32 v[50:51], v[16:17], v[40:41] op_sel_hi:[1,0]
	v_pk_fma_f32 v[46:47], v[18:19], v[144:145], v[46:47] op_sel:[0,1,0] op_sel_hi:[1,1,1]
	v_pk_fma_f32 v[50:51], v[18:19], v[40:41], v[50:51] op_sel:[0,1,0] op_sel_hi:[1,1,1]
	v_pk_fma_f32 v[46:47], v[20:21], v[146:147], v[46:47] op_sel_hi:[1,0,1]
	v_pk_fma_f32 v[50:51], v[20:21], v[42:43], v[50:51] op_sel_hi:[1,0,1]
	v_pk_fma_f32 v[46:47], v[22:23], v[146:147], v[46:47] op_sel:[0,1,0] op_sel_hi:[1,1,1]
	v_pk_fma_f32 v[50:51], v[22:23], v[42:43], v[50:51] op_sel:[0,1,0] op_sel_hi:[1,1,1]
	ds_read_b128 v[40:43], v2 offset:3584
	v_pk_fma_f32 v[16:17], v[164:165], v[156:157], v[16:17] op_sel_hi:[1,0,1]
	v_add_f32_dpp v48, v47, v46 quad_perm:[1,0,3,2] row_mask:0xf bank_mask:0xf bound_ctrl:1
	v_add_f32_dpp v52, v51, v50 quad_perm:[1,0,3,2] row_mask:0xf bank_mask:0xf bound_ctrl:1
	v_pk_fma_f32 v[18:19], v[164:165], v[156:157], v[18:19] op_sel:[0,1,0] op_sel_hi:[1,1,1]
	v_add_f32_dpp v48, v48, v48 quad_perm:[2,3,0,1] row_mask:0xf bank_mask:0xf bound_ctrl:1
	v_pk_fma_f32 v[20:21], v[164:165], v[158:159], v[20:21] op_sel_hi:[1,0,1]
	s_nop 0
	v_add_f32_dpp v48, v48, v48 row_ror:4 row_mask:0xf bank_mask:0xf bound_ctrl:1
	v_pk_fma_f32 v[22:23], v[164:165], v[158:159], v[22:23] op_sel:[0,1,0] op_sel_hi:[1,1,1]
	s_nop 0
	v_add_f32_dpp v48, v48, v48 row_ror:8 row_mask:0xf bank_mask:0xf bound_ctrl:1
	s_nop 1
	v_mov_b32_dpp v49, v48 quad_perm:[1,0,3,2] row_mask:0xf bank_mask:0xf bound_ctrl:1
	v_pk_fma_f32 v[16:17], v[48:49], v[152:153], v[16:17] op_sel_hi:[1,0,1] neg_lo:[0,1,0] neg_hi:[0,1,0]
	v_pk_fma_f32 v[18:19], v[48:49], v[152:153], v[18:19] op_sel:[0,1,0] op_sel_hi:[1,1,1] neg_lo:[0,1,0] neg_hi:[0,1,0]
	v_pk_fma_f32 v[20:21], v[48:49], v[154:155], v[20:21] op_sel_hi:[1,0,1] neg_lo:[0,1,0] neg_hi:[0,1,0]
	v_pk_fma_f32 v[22:23], v[48:49], v[154:155], v[22:23] op_sel:[0,1,0] op_sel_hi:[1,1,1] neg_lo:[0,1,0] neg_hi:[0,1,0]
	ds_read_b128 v[144:147], v2 offset:20224
	ds_read_b64 v[164:165], v3 offset:16128
	ds_read_b128 v[156:159], v2 offset:12032
	ds_read_b128 v[148:151], v2 offset:7936
	ds_read_b128 v[152:155], v2 offset:24320
	s_waitcnt lgkmcnt(5)
	v_pk_mul_f32 v[46:47], v[16:17], v[24:25] op_sel_hi:[1,0]
	v_pk_mul_f32 v[50:51], v[16:17], v[160:161] op_sel_hi:[1,0]
	v_pk_fma_f32 v[46:47], v[18:19], v[24:25], v[46:47] op_sel:[0,1,0] op_sel_hi:[1,1,1]
	v_pk_fma_f32 v[50:51], v[18:19], v[160:161], v[50:51] op_sel:[0,1,0] op_sel_hi:[1,1,1]
	v_pk_fma_f32 v[46:47], v[20:21], v[26:27], v[46:47] op_sel_hi:[1,0,1]
	v_pk_fma_f32 v[50:51], v[20:21], v[162:163], v[50:51] op_sel_hi:[1,0,1]
	v_pk_fma_f32 v[46:47], v[22:23], v[26:27], v[46:47] op_sel:[0,1,0] op_sel_hi:[1,1,1]
	v_pk_fma_f32 v[50:51], v[22:23], v[162:163], v[50:51] op_sel:[0,1,0] op_sel_hi:[1,1,1]
	ds_read_b128 v[160:163], v2 offset:3840
	v_pk_fma_f32 v[16:17], v[44:45], v[36:37], v[16:17] op_sel_hi:[1,0,1]
	v_add_f32_dpp v48, v47, v46 quad_perm:[1,0,3,2] row_mask:0xf bank_mask:0xf bound_ctrl:1
	v_add_f32_dpp v53, v51, v50 quad_perm:[1,0,3,2] row_mask:0xf bank_mask:0xf bound_ctrl:1
	v_pk_fma_f32 v[18:19], v[44:45], v[36:37], v[18:19] op_sel:[0,1,0] op_sel_hi:[1,1,1]
	v_add_f32_dpp v48, v48, v48 quad_perm:[2,3,0,1] row_mask:0xf bank_mask:0xf bound_ctrl:1
	ds_write2st64_b32 v0, v52, v53 offset0:240 offset1:244
	v_pk_fma_f32 v[20:21], v[44:45], v[38:39], v[20:21] op_sel_hi:[1,0,1]
	v_add_f32_dpp v48, v48, v48 row_ror:4 row_mask:0xf bank_mask:0xf bound_ctrl:1
	v_pk_fma_f32 v[22:23], v[44:45], v[38:39], v[22:23] op_sel:[0,1,0] op_sel_hi:[1,1,1]
	s_nop 0
	v_add_f32_dpp v48, v48, v48 row_ror:8 row_mask:0xf bank_mask:0xf bound_ctrl:1
	s_nop 1
	v_mov_b32_dpp v49, v48 quad_perm:[1,0,3,2] row_mask:0xf bank_mask:0xf bound_ctrl:1
	v_pk_fma_f32 v[16:17], v[48:49], v[32:33], v[16:17] op_sel_hi:[1,0,1] neg_lo:[0,1,0] neg_hi:[0,1,0]
	v_pk_fma_f32 v[18:19], v[48:49], v[32:33], v[18:19] op_sel:[0,1,0] op_sel_hi:[1,1,1] neg_lo:[0,1,0] neg_hi:[0,1,0]
	v_pk_fma_f32 v[20:21], v[48:49], v[34:35], v[20:21] op_sel_hi:[1,0,1] neg_lo:[0,1,0] neg_hi:[0,1,0]
	v_pk_fma_f32 v[22:23], v[48:49], v[34:35], v[22:23] op_sel:[0,1,0] op_sel_hi:[1,1,1] neg_lo:[0,1,0] neg_hi:[0,1,0]
	s_waitcnt lgkmcnt(1)
	v_pk_mul_f32 v[46:47], v[16:17], v[144:145] op_sel_hi:[1,0]
	v_pk_mul_f32 v[50:51], v[16:17], v[40:41] op_sel_hi:[1,0]
	v_pk_fma_f32 v[46:47], v[18:19], v[144:145], v[46:47] op_sel:[0,1,0] op_sel_hi:[1,1,1]
	v_pk_fma_f32 v[50:51], v[18:19], v[40:41], v[50:51] op_sel:[0,1,0] op_sel_hi:[1,1,1]
	v_pk_fma_f32 v[46:47], v[20:21], v[146:147], v[46:47] op_sel_hi:[1,0,1]
	v_pk_fma_f32 v[50:51], v[20:21], v[42:43], v[50:51] op_sel_hi:[1,0,1]
	v_pk_fma_f32 v[46:47], v[22:23], v[146:147], v[46:47] op_sel:[0,1,0] op_sel_hi:[1,1,1]
	v_pk_fma_f32 v[50:51], v[22:23], v[42:43], v[50:51] op_sel:[0,1,0] op_sel_hi:[1,1,1]
	v_pk_fma_f32 v[16:17], v[164:165], v[156:157], v[16:17] op_sel_hi:[1,0,1]
	v_add_f32_dpp v48, v47, v46 quad_perm:[1,0,3,2] row_mask:0xf bank_mask:0xf bound_ctrl:1
	v_add_f32_dpp v52, v51, v50 quad_perm:[1,0,3,2] row_mask:0xf bank_mask:0xf bound_ctrl:1
	v_pk_fma_f32 v[18:19], v[164:165], v[156:157], v[18:19] op_sel:[0,1,0] op_sel_hi:[1,1,1]
	v_add_f32_dpp v48, v48, v48 quad_perm:[2,3,0,1] row_mask:0xf bank_mask:0xf bound_ctrl:1
	v_pk_fma_f32 v[20:21], v[164:165], v[158:159], v[20:21] op_sel_hi:[1,0,1]
	s_nop 0
	v_add_f32_dpp v48, v48, v48 row_ror:4 row_mask:0xf bank_mask:0xf bound_ctrl:1
	v_pk_fma_f32 v[22:23], v[164:165], v[158:159], v[22:23] op_sel:[0,1,0] op_sel_hi:[1,1,1]
	s_nop 0
	v_add_f32_dpp v48, v48, v48 row_ror:8 row_mask:0xf bank_mask:0xf bound_ctrl:1
	s_nop 1
	v_mov_b32_dpp v49, v48 quad_perm:[1,0,3,2] row_mask:0xf bank_mask:0xf bound_ctrl:1
	v_pk_fma_f32 v[16:17], v[48:49], v[152:153], v[16:17] op_sel_hi:[1,0,1] neg_lo:[0,1,0] neg_hi:[0,1,0]
	v_pk_fma_f32 v[18:19], v[48:49], v[152:153], v[18:19] op_sel:[0,1,0] op_sel_hi:[1,1,1] neg_lo:[0,1,0] neg_hi:[0,1,0]
	v_pk_fma_f32 v[20:21], v[48:49], v[154:155], v[20:21] op_sel_hi:[1,0,1] neg_lo:[0,1,0] neg_hi:[0,1,0]
	v_pk_fma_f32 v[22:23], v[48:49], v[154:155], v[22:23] op_sel:[0,1,0] op_sel_hi:[1,1,1] neg_lo:[0,1,0] neg_hi:[0,1,0]
	v_pk_mul_f32 v[16:17], v[16:17], v[148:149] op_sel_hi:[1,0]
	v_pk_mul_f32 v[18:19], v[18:19], v[148:149] op_sel:[0,1] op_sel_hi:[1,1]
	v_pk_mul_f32 v[20:21], v[20:21], v[150:151] op_sel_hi:[1,0]
	v_pk_mul_f32 v[22:23], v[22:23], v[150:151] op_sel:[0,1] op_sel_hi:[1,1]
	v_pk_mul_f32 v[50:51], v[16:17], v[160:161] op_sel_hi:[1,0]
	v_pk_fma_f32 v[50:51], v[18:19], v[160:161], v[50:51] op_sel:[0,1,0] op_sel_hi:[1,1,1]
	v_pk_fma_f32 v[50:51], v[20:21], v[162:163], v[50:51] op_sel_hi:[1,0,1]
	v_pk_fma_f32 v[50:51], v[22:23], v[162:163], v[50:51] op_sel:[0,1,0] op_sel_hi:[1,1,1]
	s_nop 1
	v_add_f32_dpp v53, v51, v50 quad_perm:[1,0,3,2] row_mask:0xf bank_mask:0xf bound_ctrl:1
	ds_write2st64_b32 v0, v52, v53 offset0:248 offset1:252

.LBB0_550:
	s_andn2_b64 vcc, exec, s[4:5]
	s_cbranch_vccnz .LBB0_555
	v_lshlrev_b32_e32 v2, 16, v96
	v_and_b32_e32 v3, 0xffff0000, v96
	v_lshlrev_b32_e32 v32, 16, v97
	v_and_b32_e32 v33, 0xffff0000, v97
	v_pk_mul_f32 v[40:41], v[4:5], v[2:3]
	v_pk_mul_f32 v[42:43], v[6:7], v[32:33]
	v_pk_mul_f32 v[36:37], v[40:41], v[40:41]
	v_pk_mul_f32 v[34:35], v[42:43], v[42:43]
	v_lshlrev_b32_e32 v44, 16, v102
	v_pk_mov_b32 v[38:39], v[36:37], v[34:35] op_sel:[1,0]
	v_mov_b32_e32 v37, v35
	v_pk_add_f32 v[34:35], v[38:39], v[36:37]
	v_and_b32_e32 v45, 0xffff0000, v102
	v_lshlrev_b32_e32 v46, 16, v103
	v_and_b32_e32 v47, 0xffff0000, v103
	v_add_f32_e32 v0, v34, v35
	v_pk_add_f32 v[34:35], v[46:47], -1.0 op_sel_hi:[1,0]
	v_pk_add_f32 v[36:37], v[44:45], -1.0 op_sel_hi:[1,0]
	v_add_f32_dpp v0, v0, v0 quad_perm:[1,0,3,2] row_mask:0xf bank_mask:0xf bound_ctrl:1
	v_pk_fma_f32 v[36:37], v[8:9], v[36:37], 1.0 op_sel_hi:[1,1,0]
	v_pk_fma_f32 v[34:35], v[10:11], v[34:35], 1.0 op_sel_hi:[1,1,0]
	v_add_f32_dpp v0, v0, v0 quad_perm:[2,3,0,1] row_mask:0xf bank_mask:0xf bound_ctrl:1
	v_lshlrev_b32_e32 v24, 16, v94
	v_and_b32_e32 v25, 0xffff0000, v94
	v_add_f32_dpp v0, v0, v0 row_half_mirror row_mask:0xf bank_mask:0xf bound_ctrl:1
	v_pk_mul_f32 v[34:35], v[34:35], v[32:33]
	v_pk_mul_f32 v[32:33], v[36:37], v[2:3]
	v_lshlrev_b32_e32 v26, 16, v95
	v_and_b32_e32 v27, 0xffff0000, v95
	v_add_f32_dpp v0, v0, v0 row_mirror row_mask:0xf bank_mask:0xf bound_ctrl:1
	v_pk_mul_f32 v[2:3], v[32:33], v[24:25]
	v_lshlrev_b32_e32 v49, 16, v100
	v_max_f32_e32 v0, 0x179abe15, v0
	v_pk_mul_f32 v[36:37], v[34:35], v[26:27]
	v_pk_mul_f32 v[2:3], v[12:13], v[2:3]
	v_and_b32_e32 v50, 0xffff0000, v100
	v_rsq_f32_e32 v48, v0
	v_pk_mul_f32 v[36:37], v[14:15], v[36:37]
	v_add_f32_e32 v0, v2, v3
	v_mul_f32_e32 v3, 0xbfb8aa3b, v49
	v_lshlrev_b32_e32 v51, 16, v101
	v_add_f32_e32 v2, v36, v37
	v_exp_f32_e32 v36, v3
	v_mul_f32_e32 v3, 0xbfb8aa3b, v50
	v_and_b32_e32 v52, 0xffff0000, v101
	v_exp_f32_e32 v37, v3
	v_mul_f32_e32 v3, 0xbfb8aa3b, v51
	v_add_f32_e32 v0, v0, v2
	v_exp_f32_e32 v38, v3
	v_mul_f32_e32 v3, 0xbfb8aa3b, v52
	v_add_f32_dpp v0, v0, v0 quad_perm:[1,0,3,2] row_mask:0xf bank_mask:0xf bound_ctrl:1
	v_exp_f32_e32 v39, v3
	s_xor_b32 s4, s93, 1
	v_add_f32_dpp v0, v0, v0 quad_perm:[2,3,0,1] row_mask:0xf bank_mask:0xf bound_ctrl:1
	s_mulk_i32 s4, 0x6000
	v_pk_mul_f32 v[42:43], v[42:43], v[48:49] op_sel_hi:[1,0]
	v_add_f32_dpp v0, v0, v0 row_half_mirror row_mask:0xf bank_mask:0xf bound_ctrl:1
	v_pk_mul_f32 v[40:41], v[40:41], v[48:49] op_sel_hi:[1,0]
	v_add_u32_e32 v3, s4, v69
	v_lshlrev_b32_e32 v28, 16, v98
	v_and_b32_e32 v29, 0xffff0000, v98
	v_lshlrev_b32_e32 v30, 16, v99
	v_and_b32_e32 v31, 0xffff0000, v99
	v_mov_b32_dpp v2, v0 row_mirror row_mask:0xf bank_mask:0xf bound_ctrl:1
	ds_write_b128 v3, v[24:27]
	ds_write_b128 v3, v[36:39] offset:4096
	ds_write_b128 v3, v[32:35] offset:8192
	ds_write_b128 v3, v[28:31] offset:12288
	v_add_u32_e32 v197, 0x1d000, v3
	ds_write2_b32 v197, v29, v28 offset1:1
	ds_write2_b32 v197, v31, v30 offset0:2 offset1:3
	ds_write_b128 v3, v[40:43] offset:16384
	v_pk_mul_f32 v[26:27], v[42:43], v[46:47]
	v_pk_mul_f32 v[24:25], v[40:41], v[44:45]
	ds_write_b128 v3, v[24:27] offset:20480
	ds_read_b128 v[200:203], v3 offset:4096
	ds_read_b128 v[224:227], v3
	ds_read_b128 v[228:231], v3 offset:8192
	ds_read_b128 v[232:235], v3 offset:16384
	ds_read_b128 v[236:239], v3 offset:20480
	s_mov_b32 s98, 0xffff0000
	s_mov_b32 s99, 0xffff0000
	s_mov_b32 s100, 0
	s_mov_b32 s101, -1
	s_waitcnt lgkmcnt(4)
	v_mov_b32_e32 v204, v200
	v_mov_b32_e32 v205, v200
	s_nop 1
	v_permlane16_swap_b32_e32 v204, v205
	v_mul_f32_e32 v206, v204, v205
	v_bitop3_b32 v207, v204, v205, v200 bitop3:0x96
	v_cndmask_b32_e64 v207, 1.0, v207, s[98:99]
	v_mov_b32_e32 v208, v206
	v_mov_b32_e32 v209, v206
	s_nop 1
	v_permlane32_swap_b32_e32 v208, v209
	v_cndmask_b32_e64 v208, 1.0, v208, s[100:101]
	v_mul_f32_e32 v210, v207, v208
	v_mul_f32_e32 v214, v210, v200
	v_mov_b32_e32 v204, v201
	v_mov_b32_e32 v205, v201
	s_nop 1
	v_permlane16_swap_b32_e32 v204, v205
	v_mul_f32_e32 v206, v204, v205
	v_bitop3_b32 v207, v204, v205, v201 bitop3:0x96
	v_cndmask_b32_e64 v207, 1.0, v207, s[98:99]
	v_mov_b32_e32 v208, v206
	v_mov_b32_e32 v209, v206
	s_nop 1
	v_permlane32_swap_b32_e32 v208, v209
	v_cndmask_b32_e64 v208, 1.0, v208, s[100:101]
	v_mul_f32_e32 v211, v207, v208
	v_mul_f32_e32 v215, v211, v201
	v_mov_b32_e32 v204, v202
	v_mov_b32_e32 v205, v202
	s_nop 1
	v_permlane16_swap_b32_e32 v204, v205
	v_mul_f32_e32 v206, v204, v205
	v_bitop3_b32 v207, v204, v205, v202 bitop3:0x96
	v_cndmask_b32_e64 v207, 1.0, v207, s[98:99]
	v_mov_b32_e32 v208, v206
	v_mov_b32_e32 v209, v206
	s_nop 1
	v_permlane32_swap_b32_e32 v208, v209
	v_cndmask_b32_e64 v208, 1.0, v208, s[100:101]
	v_mul_f32_e32 v212, v207, v208
	v_mul_f32_e32 v216, v212, v202
	v_mov_b32_e32 v204, v203
	v_mov_b32_e32 v205, v203
	s_nop 1
	v_permlane16_swap_b32_e32 v204, v205
	v_mul_f32_e32 v206, v204, v205
	v_bitop3_b32 v207, v204, v205, v203 bitop3:0x96
	v_cndmask_b32_e64 v207, 1.0, v207, s[98:99]
	v_mov_b32_e32 v208, v206
	v_mov_b32_e32 v209, v206
	s_nop 1
	v_permlane32_swap_b32_e32 v208, v209
	v_cndmask_b32_e64 v208, 1.0, v208, s[100:101]
	v_mul_f32_e32 v213, v207, v208
	v_mul_f32_e32 v217, v213, v203
	v_rcp_f32_e32 v218, v214
	v_rcp_f32_e32 v219, v215
	v_rcp_f32_e32 v220, v216
	v_rcp_f32_e32 v221, v217
	v_cndmask_b32_e64 v204, v214, 1.0, s[98:99]
	v_cndmask_b32_e64 v240, v214, v204, s[100:101]
	v_cndmask_b32_e64 v204, v215, 1.0, s[98:99]
	v_cndmask_b32_e64 v241, v215, v204, s[100:101]
	v_cndmask_b32_e64 v204, v216, 1.0, s[98:99]
	v_cndmask_b32_e64 v242, v216, v204, s[100:101]
	v_cndmask_b32_e64 v204, v217, 1.0, s[98:99]
	v_cndmask_b32_e64 v243, v217, v204, s[100:101]
	s_waitcnt lgkmcnt(0)
	v_pk_mul_f32 v[224:225], v[224:225], v[240:241]
	v_pk_mul_f32 v[228:229], v[228:229], v[218:219]
	v_pk_mul_f32 v[232:233], v[232:233], v[210:211]
	v_pk_mul_f32 v[236:237], v[236:237], v[218:219]
	v_pk_mul_f32 v[226:227], v[226:227], v[242:243]
	v_pk_mul_f32 v[230:231], v[230:231], v[220:221]
	v_pk_mul_f32 v[234:235], v[234:235], v[212:213]
	v_pk_mul_f32 v[238:239], v[238:239], v[220:221]
	ds_write_b128 v3, v[224:227]
	ds_write_b128 v3, v[214:217] offset:4096
	ds_write_b128 v3, v[228:231] offset:8192
	ds_write_b128 v3, v[232:235] offset:16384
	ds_write_b128 v3, v[236:239] offset:20480
	s_and_saveexec_b64 s[4:5], s[2:3]
	s_cbranch_execz .LBB0_553
	v_add_u32_e32 v24, s91, v142
	v_ashrrev_i32_e32 v25, 31, v24
	v_lshlrev_b64 v[24:25], 6, v[24:25]
	v_lshl_add_u64 v[24:25], s[52:53], 0, v[24:25]
	v_add_f32_e32 v0, v0, v2
	global_store_dword v[24:25], v0, off
